# attention V^T tile stored with each lane's two 8-byte MFMA halves contiguous: conflict-free ds_read_b128 instead of 2-way-conflicted ds_read2_b64; pipelined interior-pair path in selected loop
# speedup vs baseline: 1.0517x; 1.0124x over previous
.LBB0_400:
	s_and_b32 s1, s4, 1
	s_mul_i32 s0, s1, 0x4800
	s_add_i32 s0, s0, 0
	s_lshl_b32 s1, s1, 10
	s_sub_i32 s1, s0, s1
	s_cmp_ge_i32 s8, s50
	v_add3_u32 v64, s0, v223, v224
	s_cselect_b64 s[58:59], -1, 0
	s_waitcnt vmcnt(0)
	ds_write_b128 v64, v[142:145]
	ds_write_b128 v64, v[134:137] offset:16
	v_add3_u32 v64, s1, v225, v226
	s_and_b64 vcc, exec, s[58:59]
	v_add_u32_e32 v64, 0x9000, v64
	ds_write2_b64 v64, v[138:139], v[140:141] offset1:2
	ds_write2_b64 v64, v[130:131], v[132:133] offset0:1 offset1:3
	s_waitcnt lgkmcnt(0)
	s_barrier
	s_cbranch_vccnz .LBB0_402
	v_add_u32_e32 v64, s8, v221
	v_ashrrev_i32_e32 v65, 31, v64
	v_lshlrev_b64 v[64:65], 13, v[64:65]
	v_lshl_add_u64 v[64:65], v[152:153], 0, v[64:65]
	v_ashrrev_i32_e32 v157, 31, v156
	global_load_dwordx4 v[134:137], v[64:65], off offset:16
	global_load_dwordx4 v[142:145], v[64:65], off
	v_lshl_add_u64 v[64:65], v[156:157], 1, v[154:155]
	global_load_dwordx4 v[130:133], v[64:65], off offset:16
	global_load_dwordx4 v[138:141], v[64:65], off
.LBB0_402:
	s_add_i32 s9, s8, -2
	v_add_u32_e32 v64, s0, v227
	v_add_u32_e32 v157, s1, v174
	s_cmp_lt_i32 s9, 0
	v_add_u32_e32 v160, v64, v229
	s_cbranch_scc1 .LBB0_472
	s_add_i32 s0, s8, -1
	s_cmp_lt_i32 s0, s51
	s_cbranch_scc1 .Lattn_fast0
	ds_read_b128 v[0:3], v160
	ds_read_b128 v[4:7], v160 offset:32
	ds_read_b128 v[8:11], v160 offset:64
	ds_read_b128 v[12:15], v160 offset:96
	ds_read_b128 v[16:19], v160 offset:4608
	ds_read_b128 v[20:23], v160 offset:4640
	ds_read_b128 v[24:27], v160 offset:4672
	ds_read_b128 v[28:31], v160 offset:4704
	v_lshrrev_b32_e32 v64, s9, v147
	v_and_b32_e32 v64, 1, v64
	v_cmp_eq_u32_e32 vcc, 1, v64
	s_cmp_lt_i32 s9, s51
	s_cselect_b64 s[88:89], -1, 0
	v_cndmask_b32_e32 v64, v210, v149, vcc
	v_cndmask_b32_e32 v65, v210, v151, vcc
	v_add_f32_e32 v64, v151, v64
	v_cndmask_b32_e64 v64, v65, v64, s[88:89]
	s_cmp_ge_i32 s9, s51
	s_setprio 1
	v_mov_b32_e32 v65, v64
	v_mov_b32_e32 v66, v64
	v_mov_b32_e32 v67, v64
	v_mov_b32_e32 v68, v64
	v_mov_b32_e32 v69, v64
	v_mov_b32_e32 v70, v64
	v_mov_b32_e32 v71, v64
	v_mov_b32_e32 v72, v64
	v_mov_b32_e32 v73, v64
	v_mov_b32_e32 v74, v64
	v_mov_b32_e32 v75, v64
	v_mov_b32_e32 v76, v64
	v_mov_b32_e32 v77, v64
	v_mov_b32_e32 v78, v64
	v_mov_b32_e32 v79, v64
	s_waitcnt lgkmcnt(7)
	s_nop 0
	v_mfma_f32_32x32x16_bf16 v[80:95], v[0:3], v[114:117], v[64:79]
	s_waitcnt lgkmcnt(3)
	v_mfma_f32_32x32x16_bf16 v[64:79], v[16:19], v[114:117], v[64:79]
	v_mfma_f32_32x32x16_bf16 v[80:95], v[4:7], v[118:121], v[80:95]
	s_waitcnt lgkmcnt(2)
	v_mfma_f32_32x32x16_bf16 v[64:79], v[20:23], v[118:121], v[64:79]
	v_mfma_f32_32x32x16_bf16 v[80:95], v[8:11], v[122:125], v[80:95]
	s_waitcnt lgkmcnt(1)
	v_mfma_f32_32x32x16_bf16 v[64:79], v[24:27], v[122:125], v[64:79]
	v_mfma_f32_32x32x16_bf16 v[80:95], v[12:15], v[126:129], v[80:95]
	s_waitcnt lgkmcnt(0)
	v_mfma_f32_32x32x16_bf16 v[64:79], v[28:31], v[126:129], v[64:79]
	s_setprio 0
	s_mov_b64 s[0:1], -1
	s_cbranch_scc0 .LBB0_469
	s_lshl_b32 s0, s33, 1
	s_add_i32 s0, s0, 0xfffff180
	v_lshl_add_u32 v31, v158, 2, s0
	ds_read_b32 v0, v31 offset:236
	ds_read_b32 v1, v31 offset:232
	ds_read_b32 v2, v31 offset:228
	ds_read_b32 v3, v31 offset:224
	ds_read_b32 v4, v31 offset:204
	ds_read_b32 v5, v31 offset:200
	ds_read_b32 v6, v31 offset:196
	ds_read_b32 v7, v31 offset:192
	ds_read_b32 v8, v31 offset:172
	ds_read_b32 v9, v31 offset:168
	ds_read_b32 v10, v31 offset:164
	ds_read_b32 v11, v31 offset:160
	ds_read_b32 v12, v31 offset:140
	ds_read_b32 v13, v31 offset:136
	ds_read_b32 v14, v31 offset:132
	s_waitcnt lgkmcnt(7)
	v_add_f32_e32 v0, v80, v0
	v_add_f32_e32 v1, v81, v1
	v_add_f32_e32 v2, v82, v2
	v_add_f32_e32 v3, v83, v3
	v_add_f32_e32 v4, v84, v4
	v_add_f32_e32 v5, v85, v5
	v_add_f32_e32 v6, v86, v6
	v_add_f32_e32 v7, v87, v7
	ds_read_b32 v15, v31 offset:128
	ds_read_b32 v16, v31 offset:108
	ds_read_b32 v17, v31 offset:104
	ds_read_b32 v18, v31 offset:100
	ds_read_b32 v19, v31 offset:96
	ds_read_b32 v20, v31 offset:76
	ds_read_b32 v21, v31 offset:72
	ds_read_b32 v22, v31 offset:68
	v_exp_f32_e32 v0, v0
	v_exp_f32_e32 v1, v1
	v_exp_f32_e32 v2, v2
	v_exp_f32_e32 v3, v3
	v_exp_f32_e32 v4, v4
	v_exp_f32_e32 v5, v5
	v_exp_f32_e32 v6, v6
	v_exp_f32_e32 v7, v7
	s_waitcnt lgkmcnt(8)
	v_add_f32_e32 v8, v88, v8
	v_add_f32_e32 v9, v89, v9
	v_add_f32_e32 v10, v90, v10
	v_add_f32_e32 v11, v91, v11
	v_add_f32_e32 v12, v92, v12
	v_add_f32_e32 v13, v93, v13
	v_add_f32_e32 v14, v94, v14
	ds_read_b32 v23, v31 offset:64
	ds_read_b32 v24, v31 offset:44
	ds_read_b32 v25, v31 offset:40
	ds_read_b32 v26, v31 offset:36
	ds_read_b32 v27, v31 offset:32
	ds_read_b32 v28, v31 offset:12
	ds_read_b32 v29, v31 offset:8
	v_exp_f32_e32 v8, v8
	v_add_f32_e32 v161, v159, v0
	v_exp_f32_e32 v9, v9
	v_add_f32_e32 v161, v161, v1
	v_exp_f32_e32 v10, v10
	v_add_f32_e32 v161, v161, v2
	v_exp_f32_e32 v11, v11
	v_add_f32_e32 v161, v161, v3
	v_exp_f32_e32 v12, v12
	v_add_f32_e32 v161, v161, v4
	v_exp_f32_e32 v13, v13
	v_add_f32_e32 v161, v161, v5
	v_exp_f32_e32 v14, v14
	v_add_f32_e32 v161, v161, v6
	v_add_f32_e32 v161, v161, v7
	s_waitcnt lgkmcnt(7)
	v_add_f32_e32 v15, v95, v15
	v_add_f32_e32 v16, v64, v16
	v_add_f32_e32 v17, v65, v17
	v_add_f32_e32 v18, v66, v18
	v_add_f32_e32 v19, v67, v19
	v_add_f32_e32 v20, v68, v20
	v_add_f32_e32 v21, v69, v21
	v_add_f32_e32 v22, v70, v22
	ds_read_b32 v30, v31 offset:4
	ds_read_b32 v31, v31 offset:0
	v_exp_f32_e32 v15, v15
	v_add_f32_e32 v161, v161, v8
	v_exp_f32_e32 v16, v16
	v_add_f32_e32 v161, v161, v9
	v_exp_f32_e32 v17, v17
	v_add_f32_e32 v161, v161, v10
	v_exp_f32_e32 v18, v18
	v_add_f32_e32 v161, v161, v11
	v_exp_f32_e32 v19, v19
	v_add_f32_e32 v161, v161, v12
	v_exp_f32_e32 v20, v20
	v_add_f32_e32 v161, v161, v13
	v_exp_f32_e32 v21, v21
	v_add_f32_e32 v161, v161, v14
	v_exp_f32_e32 v22, v22
	s_waitcnt lgkmcnt(2)
	v_add_f32_e32 v23, v71, v23
	v_add_f32_e32 v24, v72, v24
	v_add_f32_e32 v25, v73, v25
	v_add_f32_e32 v26, v74, v26
	v_add_f32_e32 v27, v75, v27
	v_add_f32_e32 v28, v76, v28
	v_add_f32_e32 v29, v77, v29
	v_exp_f32_e32 v23, v23
	v_add_f32_e32 v161, v161, v15
	v_exp_f32_e32 v24, v24
	v_add_f32_e32 v161, v161, v16
	v_exp_f32_e32 v25, v25
	v_add_f32_e32 v161, v161, v17
	v_exp_f32_e32 v26, v26
	v_add_f32_e32 v161, v161, v18
	v_exp_f32_e32 v27, v27
	v_add_f32_e32 v161, v161, v19
	v_exp_f32_e32 v28, v28
	v_add_f32_e32 v161, v161, v20
	v_exp_f32_e32 v29, v29
	v_add_f32_e32 v161, v161, v21
	v_add_f32_e32 v161, v161, v22
	s_waitcnt lgkmcnt(0)
	v_add_f32_e32 v30, v78, v30
	v_add_f32_e32 v31, v79, v31
	v_exp_f32_e32 v30, v30
	v_add_f32_e32 v161, v161, v23
	v_exp_f32_e32 v31, v31
	v_add_f32_e32 v161, v161, v24
	v_add_f32_e32 v161, v161, v25
	v_add_f32_e32 v161, v161, v26
	v_add_f32_e32 v161, v161, v27
	v_add_f32_e32 v161, v161, v28
	v_add_f32_e32 v161, v161, v29
	v_add_f32_e32 v161, v161, v30
	v_add_f32_e32 v161, v161, v31
	s_mov_b64 s[0:1], 0

.LBB0_471:
	s_nop 6
	v_add3_u32 v72, v157, v230, v174
	v_add_u32_e32 v80, 0x9000, v72
	v_add_u32_e32 v81, 0xb000, v72
	ds_read_b128 v[64:67], v80
	ds_read_b128 v[68:71], v80 offset:32
	ds_read_b128 v[72:75], v81 offset:512
	ds_read_b128 v[76:79], v81 offset:544
	v_cvt_pk_bf16_f32 v0, v0, v1
	v_cvt_pk_bf16_f32 v1, v2, v3
	v_cvt_pk_bf16_f32 v2, v4, v5
	v_cvt_pk_bf16_f32 v3, v6, v7
	v_cvt_pk_bf16_f32 v4, v8, v9
	v_cvt_pk_bf16_f32 v5, v10, v11
	v_cvt_pk_bf16_f32 v6, v12, v13
	v_cvt_pk_bf16_f32 v7, v14, v15
	s_setprio 1
	s_waitcnt lgkmcnt(3)
	v_mfma_f32_32x32x16_bf16 v[32:47], v[64:67], v[0:3], v[32:47]
	s_waitcnt lgkmcnt(1)
	v_mfma_f32_32x32x16_bf16 v[48:63], v[72:75], v[0:3], v[48:63]
	v_mfma_f32_32x32x16_bf16 v[32:47], v[68:71], v[4:7], v[32:47]
	s_waitcnt lgkmcnt(0)
	v_mfma_f32_32x32x16_bf16 v[48:63], v[76:79], v[4:7], v[48:63]
	s_setprio 0
	ds_read_b128 v[0:3], v80 offset:64
	ds_read_b128 v[4:7], v80 offset:96
	ds_read_b128 v[8:11], v81 offset:576
	ds_read_b128 v[12:15], v81 offset:608
	v_cvt_pk_bf16_f32 v16, v16, v17
	v_cvt_pk_bf16_f32 v17, v18, v19
	v_cvt_pk_bf16_f32 v18, v20, v21
	v_cvt_pk_bf16_f32 v19, v22, v23
	v_cvt_pk_bf16_f32 v20, v24, v25
	v_cvt_pk_bf16_f32 v21, v26, v27
	v_cvt_pk_bf16_f32 v22, v28, v29
	v_cvt_pk_bf16_f32 v23, v30, v31
	s_setprio 1
	s_waitcnt lgkmcnt(3)
	v_mfma_f32_32x32x16_bf16 v[32:47], v[0:3], v[16:19], v[32:47]
	s_waitcnt lgkmcnt(1)
	v_mfma_f32_32x32x16_bf16 v[48:63], v[8:11], v[16:19], v[48:63]
	v_mfma_f32_32x32x16_bf16 v[32:47], v[4:7], v[20:23], v[32:47]
	s_waitcnt lgkmcnt(0)
	v_mfma_f32_32x32x16_bf16 v[48:63], v[12:15], v[20:23], v[48:63]
	s_setprio 0
	s_nop 8
	v_mov_b64_e32 v[0:1], v[32:33]
	v_mov_b64_e32 v[2:3], v[34:35]
	v_mov_b64_e32 v[4:5], v[36:37]
	v_mov_b64_e32 v[6:7], v[38:39]
	v_mov_b64_e32 v[8:9], v[40:41]
	v_mov_b64_e32 v[10:11], v[42:43]
	v_mov_b64_e32 v[12:13], v[44:45]
	v_mov_b64_e32 v[14:15], v[46:47]
	v_mov_b64_e32 v[16:17], v[48:49]
	v_mov_b64_e32 v[18:19], v[50:51]
	v_mov_b64_e32 v[20:21], v[52:53]
	v_mov_b64_e32 v[22:23], v[54:55]
	v_mov_b64_e32 v[24:25], v[56:57]
	v_mov_b64_e32 v[26:27], v[58:59]
	v_mov_b64_e32 v[28:29], v[60:61]
	v_mov_b64_e32 v[30:31], v[62:63]
	s_branch .LBB0_473

.LBB0_541:
	s_nop 5
	v_add3_u32 v72, v157, v230, v174
	v_add_u32_e32 v80, 0x9000, v72
	v_add_u32_e32 v81, 0xb000, v72
	ds_read_b128 v[64:67], v80 offset:128
	ds_read_b128 v[68:71], v80 offset:160
	ds_read_b128 v[72:75], v81 offset:640
	ds_read_b128 v[76:79], v81 offset:672
	v_cvt_pk_bf16_f32 v32, v32, v33
	v_cvt_pk_bf16_f32 v33, v34, v35
	v_cvt_pk_bf16_f32 v34, v36, v37
	v_cvt_pk_bf16_f32 v35, v38, v39
	v_cvt_pk_bf16_f32 v36, v40, v41
	v_cvt_pk_bf16_f32 v37, v42, v43
	v_cvt_pk_bf16_f32 v38, v44, v45
	v_cvt_pk_bf16_f32 v39, v46, v47
	s_setprio 1
	s_waitcnt lgkmcnt(3)
	v_mfma_f32_32x32x16_bf16 v[0:15], v[64:67], v[32:35], v[0:15]
	s_waitcnt lgkmcnt(1)
	v_mfma_f32_32x32x16_bf16 v[16:31], v[72:75], v[32:35], v[16:31]
	v_mfma_f32_32x32x16_bf16 v[0:15], v[68:71], v[36:39], v[0:15]
	s_waitcnt lgkmcnt(0)
	v_mfma_f32_32x32x16_bf16 v[16:31], v[76:79], v[36:39], v[16:31]
	s_setprio 0
	ds_read_b128 v[32:35], v80 offset:192
	ds_read_b128 v[36:39], v80 offset:224
	ds_read_b128 v[40:43], v81 offset:704
	ds_read_b128 v[44:47], v81 offset:736
	v_cvt_pk_bf16_f32 v48, v48, v49
	v_cvt_pk_bf16_f32 v49, v50, v51
	v_cvt_pk_bf16_f32 v50, v52, v53
	v_cvt_pk_bf16_f32 v51, v54, v55
	v_cvt_pk_bf16_f32 v52, v56, v57
	v_cvt_pk_bf16_f32 v53, v58, v59
	v_cvt_pk_bf16_f32 v54, v60, v61
	v_cvt_pk_bf16_f32 v55, v62, v63
	s_setprio 1
	s_waitcnt lgkmcnt(3)
	v_mfma_f32_32x32x16_bf16 v[0:15], v[32:35], v[48:51], v[0:15]
	s_waitcnt lgkmcnt(1)
	v_mfma_f32_32x32x16_bf16 v[16:31], v[40:43], v[48:51], v[16:31]
	v_mfma_f32_32x32x16_bf16 v[0:15], v[36:39], v[52:55], v[0:15]
	s_waitcnt lgkmcnt(0)
	v_mfma_f32_32x32x16_bf16 v[16:31], v[44:47], v[52:55], v[16:31]
	s_setprio 0
	s_add_i32 s4, s4, 1
	v_add_u32_e32 v158, 0xffffff80, v158
	s_add_i32 s8, s8, 2
	s_andn2_b64 vcc, exec, s[58:59]
	v_add_u32_e32 v156, 0x80, v156
	s_cbranch_vccz .LBB0_543
	s_nop 2
	v_mov_b32_e32 v32, v0
	v_mov_b32_e32 v33, v1
	v_mov_b32_e32 v34, v2
	v_mov_b32_e32 v35, v3
	v_mov_b32_e32 v36, v4
	v_mov_b32_e32 v37, v5
	v_mov_b32_e32 v38, v6
	v_mov_b32_e32 v39, v7
	v_mov_b32_e32 v40, v8
	v_mov_b32_e32 v41, v9
	v_mov_b32_e32 v42, v10
	v_mov_b32_e32 v43, v11
	v_mov_b32_e32 v44, v12
	v_mov_b32_e32 v45, v13
	v_mov_b32_e32 v46, v14
	v_mov_b32_e32 v47, v15
	v_mov_b32_e32 v48, v16
	v_mov_b32_e32 v49, v17
	v_mov_b32_e32 v50, v18
	v_mov_b32_e32 v51, v19
	v_mov_b32_e32 v52, v20
	v_mov_b32_e32 v53, v21
	v_mov_b32_e32 v54, v22
	v_mov_b32_e32 v55, v23
	v_mov_b32_e32 v56, v24
	v_mov_b32_e32 v57, v25
	v_mov_b32_e32 v58, v26
	v_mov_b32_e32 v59, v27
	v_mov_b32_e32 v60, v28
	v_mov_b32_e32 v61, v29
	v_mov_b32_e32 v62, v30
	v_mov_b32_e32 v63, v31
	s_branch .LBB0_400
.Lattn_fast0:
	ds_read_b128 v[0:3], v160
	ds_read_b128 v[4:7], v160 offset:32
	ds_read_b128 v[8:11], v160 offset:64
	ds_read_b128 v[12:15], v160 offset:96
	ds_read_b128 v[16:19], v160 offset:4608
	ds_read_b128 v[20:23], v160 offset:4640
	ds_read_b128 v[24:27], v160 offset:4672
	ds_read_b128 v[28:31], v160 offset:4704
	v_lshrrev_b32_e32 v64, s9, v147
	v_lshrrev_b32_e32 v204, s0, v147
	v_and_b32_e32 v64, 1, v64
	v_and_b32_e32 v204, 1, v204
	v_cmp_eq_u32_e32 vcc, 1, v64
	v_cmp_eq_u32_e64 s[88:89], 1, v204
	v_add3_u32 v162, v157, v230, v174
	v_add_u32_e32 v165, 0xb000, v162
	v_cndmask_b32_e32 v64, v210, v149, vcc
	v_cndmask_b32_e64 v204, v210, v149, s[88:89]
	v_add_f32_e32 v64, v151, v64
	v_add_f32_e32 v204, v151, v204
	v_add_u32_e32 v162, 0x9000, v162
	v_mov_b32_e32 v65, v64
	v_mov_b32_e32 v66, v64
	v_mov_b32_e32 v67, v64
	v_mov_b32_e32 v68, v64
	v_mov_b32_e32 v69, v64
	v_mov_b32_e32 v70, v64
	v_mov_b32_e32 v71, v64
	v_mov_b32_e32 v72, v64
	v_mov_b32_e32 v73, v64
	v_mov_b32_e32 v74, v64
	v_mov_b32_e32 v75, v64
	v_mov_b32_e32 v76, v64
	v_mov_b32_e32 v77, v64
	v_mov_b32_e32 v78, v64
	v_mov_b32_e32 v79, v64
	ds_read_b128 v[98:101], v160 offset:9216
	ds_read_b128 v[102:105], v160 offset:9248
	ds_read_b128 v[106:109], v160 offset:9280
	ds_read_b128 v[110:113], v160 offset:9312
	s_waitcnt lgkmcnt(11)
	v_mfma_f32_32x32x16_bf16 v[80:95], v[0:3], v[114:117], v[64:79]
	s_waitcnt lgkmcnt(7)
	v_mfma_f32_32x32x16_bf16 v[64:79], v[16:19], v[114:117], v[64:79]
	v_mfma_f32_32x32x16_bf16 v[80:95], v[4:7], v[118:121], v[80:95]
	s_waitcnt lgkmcnt(6)
	v_mfma_f32_32x32x16_bf16 v[64:79], v[20:23], v[118:121], v[64:79]
	v_mfma_f32_32x32x16_bf16 v[80:95], v[8:11], v[122:125], v[80:95]
	s_waitcnt lgkmcnt(5)
	v_mfma_f32_32x32x16_bf16 v[64:79], v[24:27], v[122:125], v[64:79]
	v_mfma_f32_32x32x16_bf16 v[80:95], v[12:15], v[126:129], v[80:95]
	s_waitcnt lgkmcnt(4)
	v_mfma_f32_32x32x16_bf16 v[64:79], v[28:31], v[126:129], v[64:79]
	v_mov_b32_e32 v0, v204
	v_mov_b32_e32 v1, v204
	v_mov_b32_e32 v2, v204
	v_mov_b32_e32 v3, v204
	v_mov_b32_e32 v4, v204
	v_mov_b32_e32 v5, v204
	v_mov_b32_e32 v6, v204
	v_mov_b32_e32 v7, v204
	v_mov_b32_e32 v8, v204
	v_mov_b32_e32 v9, v204
	v_mov_b32_e32 v10, v204
	v_mov_b32_e32 v11, v204
	v_mov_b32_e32 v12, v204
	v_mov_b32_e32 v13, v204
	v_mov_b32_e32 v14, v204
	v_mov_b32_e32 v15, v204
	v_exp_f32_e32 v80, v80
	v_exp_f32_e32 v81, v81
	v_add_f32_e32 v161, v159, v80
	v_exp_f32_e32 v82, v82
	s_waitcnt lgkmcnt(3)
	v_mfma_f32_32x32x16_bf16 v[16:31], v[98:101], v[114:117], v[0:15]
	v_add_f32_e32 v161, v161, v81
	v_exp_f32_e32 v83, v83
	v_add_f32_e32 v161, v161, v82
	v_exp_f32_e32 v84, v84
	v_add_f32_e32 v161, v161, v83
	v_exp_f32_e32 v85, v85
	v_add_f32_e32 v161, v161, v84
	v_exp_f32_e32 v86, v86
	s_waitcnt lgkmcnt(2)
	v_mfma_f32_32x32x16_bf16 v[16:31], v[102:105], v[118:121], v[16:31]
	v_add_f32_e32 v161, v161, v85
	v_exp_f32_e32 v87, v87
	v_add_f32_e32 v161, v161, v86
	v_exp_f32_e32 v88, v88
	v_add_f32_e32 v161, v161, v87
	v_exp_f32_e32 v89, v89
	v_add_f32_e32 v161, v161, v88
	v_exp_f32_e32 v90, v90
	s_waitcnt lgkmcnt(1)
	v_mfma_f32_32x32x16_bf16 v[16:31], v[106:109], v[122:125], v[16:31]
	v_add_f32_e32 v161, v161, v89
	v_exp_f32_e32 v91, v91
	v_add_f32_e32 v161, v161, v90
	v_exp_f32_e32 v92, v92
	v_add_f32_e32 v161, v161, v91
	v_exp_f32_e32 v93, v93
	v_add_f32_e32 v161, v161, v92
	v_exp_f32_e32 v94, v94
	s_waitcnt lgkmcnt(0)
	v_mfma_f32_32x32x16_bf16 v[16:31], v[110:113], v[126:129], v[16:31]
	ds_read_b128 v[98:101], v160 offset:13824
	ds_read_b128 v[102:105], v160 offset:13856
	ds_read_b128 v[106:109], v160 offset:13888
	ds_read_b128 v[110:113], v160 offset:13920
	v_add_f32_e32 v161, v161, v93
	v_exp_f32_e32 v95, v95
	v_add_f32_e32 v161, v161, v94
	v_exp_f32_e32 v64, v64
	v_add_f32_e32 v161, v161, v95
	v_exp_f32_e32 v65, v65
	v_add_f32_e32 v161, v161, v64
	v_exp_f32_e32 v66, v66
	v_add_f32_e32 v161, v161, v65
	v_exp_f32_e32 v67, v67
	v_add_f32_e32 v161, v161, v66
	v_exp_f32_e32 v68, v68
	s_waitcnt lgkmcnt(3)
	v_mfma_f32_32x32x16_bf16 v[0:15], v[98:101], v[114:117], v[0:15]
	v_add_f32_e32 v161, v161, v67
	v_exp_f32_e32 v69, v69
	v_add_f32_e32 v161, v161, v68
	v_exp_f32_e32 v70, v70
	v_add_f32_e32 v161, v161, v69
	v_exp_f32_e32 v71, v71
	v_add_f32_e32 v161, v161, v70
	v_exp_f32_e32 v72, v72
	s_waitcnt lgkmcnt(2)
	v_mfma_f32_32x32x16_bf16 v[0:15], v[102:105], v[118:121], v[0:15]
	v_add_f32_e32 v161, v161, v71
	v_exp_f32_e32 v73, v73
	v_add_f32_e32 v161, v161, v72
	v_exp_f32_e32 v74, v74
	v_add_f32_e32 v161, v161, v73
	v_exp_f32_e32 v75, v75
	v_add_f32_e32 v161, v161, v74
	v_exp_f32_e32 v76, v76
	s_waitcnt lgkmcnt(1)
	v_mfma_f32_32x32x16_bf16 v[0:15], v[106:109], v[122:125], v[0:15]
	v_add_f32_e32 v161, v161, v75
	v_exp_f32_e32 v77, v77
	v_add_f32_e32 v161, v161, v76
	v_exp_f32_e32 v78, v78
	v_add_f32_e32 v161, v161, v77
	v_exp_f32_e32 v79, v79
	v_add_f32_e32 v161, v161, v78
	v_add_f32_e32 v161, v161, v79
	s_waitcnt lgkmcnt(0)
	v_mfma_f32_32x32x16_bf16 v[0:15], v[110:113], v[126:129], v[0:15]
	ds_read_b128 v[98:101], v162
	ds_read_b128 v[102:105], v162 offset:32
	ds_read_b128 v[106:109], v165 offset:512
	ds_read_b128 v[110:113], v165 offset:544
	v_cvt_pk_bf16_f32 v80, v80, v81
	v_cvt_pk_bf16_f32 v81, v82, v83
	v_cvt_pk_bf16_f32 v82, v84, v85
	v_cvt_pk_bf16_f32 v83, v86, v87
	v_cvt_pk_bf16_f32 v84, v88, v89
	v_cvt_pk_bf16_f32 v85, v90, v91
	v_cvt_pk_bf16_f32 v86, v92, v93
	v_cvt_pk_bf16_f32 v87, v94, v95
	v_exp_f32_e32 v16, v16
	v_exp_f32_e32 v17, v17
	s_waitcnt lgkmcnt(3)
	v_mfma_f32_32x32x16_bf16 v[32:47], v[98:101], v[80:83], v[32:47]
	v_add_f32_e32 v159, v161, v16
	v_exp_f32_e32 v18, v18
	v_add_f32_e32 v159, v159, v17
	v_exp_f32_e32 v19, v19
	v_add_f32_e32 v159, v159, v18
	v_exp_f32_e32 v20, v20
	v_add_f32_e32 v159, v159, v19
	v_exp_f32_e32 v21, v21
	s_waitcnt lgkmcnt(1)
	v_mfma_f32_32x32x16_bf16 v[48:63], v[106:109], v[80:83], v[48:63]
	v_add_f32_e32 v159, v159, v20
	v_exp_f32_e32 v22, v22
	v_add_f32_e32 v159, v159, v21
	v_exp_f32_e32 v23, v23
	v_add_f32_e32 v159, v159, v22
	v_exp_f32_e32 v24, v24
	v_add_f32_e32 v159, v159, v23
	v_exp_f32_e32 v25, v25
	v_mfma_f32_32x32x16_bf16 v[32:47], v[102:105], v[84:87], v[32:47]
	v_add_f32_e32 v159, v159, v24
	v_exp_f32_e32 v26, v26
	v_add_f32_e32 v159, v159, v25
	v_exp_f32_e32 v27, v27
	v_add_f32_e32 v159, v159, v26
	v_exp_f32_e32 v28, v28
	v_add_f32_e32 v159, v159, v27
	v_exp_f32_e32 v29, v29
	s_waitcnt lgkmcnt(0)
	v_mfma_f32_32x32x16_bf16 v[48:63], v[110:113], v[84:87], v[48:63]
	ds_read_b128 v[98:101], v162 offset:64
	ds_read_b128 v[102:105], v162 offset:96
	ds_read_b128 v[106:109], v165 offset:576
	ds_read_b128 v[110:113], v165 offset:608
	v_cvt_pk_bf16_f32 v64, v64, v65
	v_cvt_pk_bf16_f32 v65, v66, v67
	v_cvt_pk_bf16_f32 v66, v68, v69
	v_cvt_pk_bf16_f32 v67, v70, v71
	v_cvt_pk_bf16_f32 v68, v72, v73
	v_cvt_pk_bf16_f32 v69, v74, v75
	v_cvt_pk_bf16_f32 v70, v76, v77
	v_cvt_pk_bf16_f32 v71, v78, v79
	v_add_f32_e32 v159, v159, v28
	v_exp_f32_e32 v30, v30
	v_add_f32_e32 v159, v159, v29
	v_exp_f32_e32 v31, v31
	v_add_f32_e32 v159, v159, v30
	v_exp_f32_e32 v0, v0
	v_add_f32_e32 v159, v159, v31
	v_exp_f32_e32 v1, v1
	s_waitcnt lgkmcnt(3)
	v_mfma_f32_32x32x16_bf16 v[32:47], v[98:101], v[64:67], v[32:47]
	v_add_f32_e32 v159, v159, v0
	v_exp_f32_e32 v2, v2
	v_add_f32_e32 v159, v159, v1
	v_exp_f32_e32 v3, v3
	v_add_f32_e32 v159, v159, v2
	v_exp_f32_e32 v4, v4
	v_add_f32_e32 v159, v159, v3
	v_exp_f32_e32 v5, v5
	s_waitcnt lgkmcnt(1)
	v_mfma_f32_32x32x16_bf16 v[48:63], v[106:109], v[64:67], v[48:63]
	v_add_f32_e32 v159, v159, v4
	v_exp_f32_e32 v6, v6
	v_add_f32_e32 v159, v159, v5
	v_exp_f32_e32 v7, v7
	v_add_f32_e32 v159, v159, v6
	v_exp_f32_e32 v8, v8
	v_add_f32_e32 v159, v159, v7
	v_exp_f32_e32 v9, v9
	v_mfma_f32_32x32x16_bf16 v[32:47], v[102:105], v[68:71], v[32:47]
	v_add_f32_e32 v159, v159, v8
	v_exp_f32_e32 v10, v10
	v_add_f32_e32 v159, v159, v9
	v_exp_f32_e32 v11, v11
	v_add_f32_e32 v159, v159, v10
	v_exp_f32_e32 v12, v12
	v_add_f32_e32 v159, v159, v11
	v_exp_f32_e32 v13, v13
	s_waitcnt lgkmcnt(0)
	v_mfma_f32_32x32x16_bf16 v[48:63], v[110:113], v[68:71], v[48:63]
	v_add_f32_e32 v159, v159, v12
	v_exp_f32_e32 v14, v14
	v_add_f32_e32 v159, v159, v13
	v_exp_f32_e32 v15, v15
	v_add_f32_e32 v159, v159, v14
	v_add_f32_e32 v159, v159, v15
	ds_read_b128 v[98:101], v162 offset:128
	ds_read_b128 v[102:105], v162 offset:160
	ds_read_b128 v[106:109], v165 offset:640
	ds_read_b128 v[110:113], v165 offset:672
	v_cvt_pk_bf16_f32 v16, v16, v17
	v_cvt_pk_bf16_f32 v17, v18, v19
	v_cvt_pk_bf16_f32 v18, v20, v21
	v_cvt_pk_bf16_f32 v19, v22, v23
	v_cvt_pk_bf16_f32 v20, v24, v25
	v_cvt_pk_bf16_f32 v21, v26, v27
	v_cvt_pk_bf16_f32 v22, v28, v29
	v_cvt_pk_bf16_f32 v23, v30, v31
	s_nop 0
	s_waitcnt lgkmcnt(3)
	v_mfma_f32_32x32x16_bf16 v[32:47], v[98:101], v[16:19], v[32:47]
	s_waitcnt lgkmcnt(1)
	v_mfma_f32_32x32x16_bf16 v[48:63], v[106:109], v[16:19], v[48:63]
	v_mfma_f32_32x32x16_bf16 v[32:47], v[102:105], v[20:23], v[32:47]
	s_waitcnt lgkmcnt(0)
	v_mfma_f32_32x32x16_bf16 v[48:63], v[110:113], v[20:23], v[48:63]
	ds_read_b128 v[98:101], v162 offset:192
	ds_read_b128 v[102:105], v162 offset:224
	ds_read_b128 v[106:109], v165 offset:704
	ds_read_b128 v[110:113], v165 offset:736
	v_cvt_pk_bf16_f32 v0, v0, v1
	v_cvt_pk_bf16_f32 v1, v2, v3
	v_cvt_pk_bf16_f32 v2, v4, v5
	v_cvt_pk_bf16_f32 v3, v6, v7
	v_cvt_pk_bf16_f32 v4, v8, v9
	v_cvt_pk_bf16_f32 v5, v10, v11
	v_cvt_pk_bf16_f32 v6, v12, v13
	v_cvt_pk_bf16_f32 v7, v14, v15
	s_nop 0
	s_waitcnt lgkmcnt(3)
	v_mfma_f32_32x32x16_bf16 v[32:47], v[98:101], v[0:3], v[32:47]
	s_waitcnt lgkmcnt(1)
	v_mfma_f32_32x32x16_bf16 v[48:63], v[106:109], v[0:3], v[48:63]
	v_mfma_f32_32x32x16_bf16 v[32:47], v[102:105], v[4:7], v[32:47]
	s_waitcnt lgkmcnt(0)
	v_mfma_f32_32x32x16_bf16 v[48:63], v[110:113], v[4:7], v[48:63]
	s_add_i32 s4, s4, 1
	v_add_u32_e32 v158, 0xffffff80, v158
	s_add_i32 s8, s8, 2
	s_andn2_b64 vcc, exec, s[58:59]
	v_add_u32_e32 v156, 0x80, v156
	s_cbranch_vccnz .LBB0_400
	s_nop 7
	v_mov_b32_e32 v0, v32
	v_mov_b32_e32 v1, v33
	v_mov_b32_e32 v2, v34
	v_mov_b32_e32 v3, v35
	v_mov_b32_e32 v4, v36
	v_mov_b32_e32 v5, v37
	v_mov_b32_e32 v6, v38
	v_mov_b32_e32 v7, v39
	v_mov_b32_e32 v8, v40
	v_mov_b32_e32 v9, v41
	v_mov_b32_e32 v10, v42
	v_mov_b32_e32 v11, v43
	v_mov_b32_e32 v12, v44
	v_mov_b32_e32 v13, v45
	v_mov_b32_e32 v14, v46
	v_mov_b32_e32 v15, v47
	v_mov_b32_e32 v16, v48
	v_mov_b32_e32 v17, v49
	v_mov_b32_e32 v18, v50
	v_mov_b32_e32 v19, v51
	v_mov_b32_e32 v20, v52
	v_mov_b32_e32 v21, v53
	v_mov_b32_e32 v22, v54
	v_mov_b32_e32 v23, v55
	v_mov_b32_e32 v24, v56
	v_mov_b32_e32 v25, v57
	v_mov_b32_e32 v26, v58
	v_mov_b32_e32 v27, v59
	v_mov_b32_e32 v28, v60
	v_mov_b32_e32 v29, v61
	v_mov_b32_e32 v30, v62
	v_mov_b32_e32 v31, v63
	s_branch .LBB0_543

.LBB0_545:
	s_and_b32 s1, s5, 1
	s_mul_i32 s0, s1, 0x4800
	s_add_i32 s0, s0, 0
	s_lshl_b32 s1, s1, 10
	s_sub_i32 s1, s0, s1
	s_add_i32 s6, s8, 2
	s_cmp_ge_i32 s6, s50
	v_add3_u32 v0, s0, v223, v224
	s_cselect_b64 s[58:59], -1, 0
	s_waitcnt vmcnt(0)
	ds_write_b128 v0, v[142:145]
	ds_write_b128 v0, v[134:137] offset:16
	v_add3_u32 v0, s1, v225, v226
	s_and_b64 vcc, exec, s[58:59]
	v_add_u32_e32 v0, 0x9000, v0
	ds_write2_b64 v0, v[138:139], v[140:141] offset1:2
	ds_write2_b64 v0, v[130:131], v[132:133] offset0:1 offset1:3
	s_waitcnt lgkmcnt(0)
	s_barrier
	s_cbranch_vccnz .LBB0_547
	v_add_u32_e32 v0, s6, v221
	v_ashrrev_i32_e32 v1, 31, v0
	v_lshlrev_b64 v[0:1], 13, v[0:1]
	v_lshl_add_u64 v[0:1], v[146:147], 0, v[0:1]
	global_load_dwordx4 v[134:137], v[0:1], off offset:16
	global_load_dwordx4 v[142:145], v[0:1], off
	v_add_lshl_u32 v0, s6, v222, 6
	v_ashrrev_i32_e32 v1, 31, v0
	v_lshl_add_u64 v[0:1], v[0:1], 1, v[148:149]
	global_load_dwordx4 v[130:133], v[0:1], off offset:16
	global_load_dwordx4 v[138:141], v[0:1], off

.LBB0_619:
	s_nop 5
	v_add3_u32 v72, v152, v230, v174
	v_add_u32_e32 v80, 0x9000, v72
	v_add_u32_e32 v81, 0xb000, v72
	ds_read_b128 v[64:67], v80
	ds_read_b128 v[68:71], v80 offset:32
	ds_read_b128 v[72:75], v81 offset:512
	ds_read_b128 v[76:79], v81 offset:544
	v_cvt_pk_bf16_f32 v0, v0, v1
	v_cvt_pk_bf16_f32 v1, v2, v3
	v_cvt_pk_bf16_f32 v2, v4, v5
	v_cvt_pk_bf16_f32 v3, v6, v7
	v_cvt_pk_bf16_f32 v4, v8, v9
	v_cvt_pk_bf16_f32 v5, v10, v11
	v_cvt_pk_bf16_f32 v6, v12, v13
	v_cvt_pk_bf16_f32 v7, v14, v15
	s_setprio 1
	s_waitcnt lgkmcnt(3)
	v_mfma_f32_32x32x16_bf16 v[48:63], v[64:67], v[0:3], v[48:63]
	s_waitcnt lgkmcnt(1)
	v_mfma_f32_32x32x16_bf16 v[32:47], v[72:75], v[0:3], v[32:47]
	v_mfma_f32_32x32x16_bf16 v[48:63], v[68:71], v[4:7], v[48:63]
	s_waitcnt lgkmcnt(0)
	v_mfma_f32_32x32x16_bf16 v[32:47], v[76:79], v[4:7], v[32:47]
	s_setprio 0
	ds_read_b128 v[0:3], v80 offset:64
	ds_read_b128 v[4:7], v80 offset:96
	ds_read_b128 v[8:11], v81 offset:576
	ds_read_b128 v[12:15], v81 offset:608
	v_cvt_pk_bf16_f32 v16, v16, v17
	v_cvt_pk_bf16_f32 v17, v18, v19
	v_cvt_pk_bf16_f32 v18, v20, v21
	v_cvt_pk_bf16_f32 v19, v22, v23
	v_cvt_pk_bf16_f32 v20, v24, v25
	v_cvt_pk_bf16_f32 v21, v26, v27
	v_cvt_pk_bf16_f32 v22, v28, v29
	v_cvt_pk_bf16_f32 v23, v30, v31
	s_setprio 1
	s_waitcnt lgkmcnt(3)
	v_mfma_f32_32x32x16_bf16 v[48:63], v[0:3], v[16:19], v[48:63]
	s_waitcnt lgkmcnt(1)
	v_mfma_f32_32x32x16_bf16 v[32:47], v[8:11], v[16:19], v[32:47]
	v_mfma_f32_32x32x16_bf16 v[48:63], v[4:7], v[20:23], v[48:63]
	s_waitcnt lgkmcnt(0)
	v_mfma_f32_32x32x16_bf16 v[32:47], v[12:15], v[20:23], v[32:47]
	s_setprio 0
	v_mov_b32_e32 v153, v156
	s_add_i32 s7, s8, 1
	s_cmp_lt_u32 s7, s4
	s_cbranch_scc0 .LBB0_622

.LBB0_693:
	s_nop 5
	v_add3_u32 v72, v152, v230, v174
	v_add_u32_e32 v80, 0x9000, v72
	v_add_u32_e32 v81, 0xb000, v72
	ds_read_b128 v[64:67], v80 offset:128
	ds_read_b128 v[68:71], v80 offset:160
	ds_read_b128 v[72:75], v81 offset:640
	ds_read_b128 v[76:79], v81 offset:672
	v_cvt_pk_bf16_f32 v0, v0, v1
	v_cvt_pk_bf16_f32 v1, v2, v3
	v_cvt_pk_bf16_f32 v2, v4, v5
	v_cvt_pk_bf16_f32 v3, v6, v7
	v_cvt_pk_bf16_f32 v4, v8, v9
	v_cvt_pk_bf16_f32 v5, v10, v11
	v_cvt_pk_bf16_f32 v6, v12, v13
	v_cvt_pk_bf16_f32 v7, v14, v15
	s_setprio 1
	s_waitcnt lgkmcnt(3)
	v_mfma_f32_32x32x16_bf16 v[48:63], v[64:67], v[0:3], v[48:63]
	s_waitcnt lgkmcnt(1)
	v_mfma_f32_32x32x16_bf16 v[32:47], v[72:75], v[0:3], v[32:47]
	v_mfma_f32_32x32x16_bf16 v[48:63], v[68:71], v[4:7], v[48:63]
	s_waitcnt lgkmcnt(0)
	v_mfma_f32_32x32x16_bf16 v[32:47], v[76:79], v[4:7], v[32:47]
	s_setprio 0
	ds_read_b128 v[0:3], v80 offset:192
	ds_read_b128 v[4:7], v80 offset:224
	ds_read_b128 v[8:11], v81 offset:704
	ds_read_b128 v[12:15], v81 offset:736
	v_cvt_pk_bf16_f32 v16, v16, v17
	v_cvt_pk_bf16_f32 v17, v18, v19
	v_cvt_pk_bf16_f32 v18, v20, v21
	v_cvt_pk_bf16_f32 v19, v22, v23
	v_cvt_pk_bf16_f32 v20, v24, v25
	v_cvt_pk_bf16_f32 v21, v26, v27
	v_cvt_pk_bf16_f32 v22, v28, v29
	v_cvt_pk_bf16_f32 v23, v30, v31
	s_setprio 1
	s_waitcnt lgkmcnt(3)
	v_mfma_f32_32x32x16_bf16 v[48:63], v[0:3], v[16:19], v[48:63]
	s_waitcnt lgkmcnt(1)
	v_mfma_f32_32x32x16_bf16 v[32:47], v[8:11], v[16:19], v[32:47]
	v_mfma_f32_32x32x16_bf16 v[48:63], v[4:7], v[20:23], v[48:63]
	s_waitcnt lgkmcnt(0)
	v_mfma_f32_32x32x16_bf16 v[32:47], v[12:15], v[20:23], v[32:47]
	s_setprio 0
	v_mov_b32_e32 v153, v155
	s_andn2_b64 vcc, exec, s[58:59]
	s_add_i32 s5, s5, 1
	s_cbranch_vccz .LBB0_695

.LBB0_916:
	s_or_b64 exec, exec, s[0:1]
	s_waitcnt lgkmcnt(14)
	v_cvt_pk_bf16_f32 v0, v1, v0
	v_cvt_pk_bf16_f32 v1, v3, v2
	v_cvt_pk_bf16_f32 v2, v190, v189
	s_waitcnt lgkmcnt(1)
	v_mul_f32_e32 v190, v89, v85
	v_cvt_pk_bf16_f32 v3, v192, v191
	v_pk_fma_f32 v[190:191], v[88:89], v[84:85], v[190:191] op_sel_hi:[1,1,0] neg_lo:[0,0,1] neg_hi:[0,0,1]
	v_pk_mul_f32 v[84:85], v[88:89], v[84:85] op_sel:[1,0] op_sel_hi:[0,1]
	v_add_f32_e32 v84, v84, v85
	v_xor_b32_e32 v88, 0x80000000, v84
	v_mul_f32_e32 v84, v91, v87
	v_pk_fma_f32 v[84:85], v[90:91], v[86:87], v[84:85] op_sel_hi:[1,1,0] neg_lo:[0,0,1] neg_hi:[0,0,1]
	v_pk_mul_f32 v[86:87], v[90:91], v[86:87] op_sel:[1,0] op_sel_hi:[0,1]
	v_add_f32_e32 v85, v86, v87
	v_mul_f32_e32 v86, v5, v81
	v_pk_fma_f32 v[86:87], v[4:5], v[80:81], v[86:87] op_sel_hi:[1,1,0] neg_lo:[0,0,1] neg_hi:[0,0,1]
	v_pk_mul_f32 v[4:5], v[4:5], v[80:81] op_sel:[1,0] op_sel_hi:[0,1]
	v_add_f32_e32 v4, v4, v5
	v_xor_b32_e32 v87, 0x80000000, v4
	v_mul_f32_e32 v4, v7, v83
	v_pk_fma_f32 v[80:81], v[6:7], v[82:83], v[4:5] op_sel_hi:[1,1,0] neg_lo:[0,0,1] neg_hi:[0,0,1]
	v_pk_mul_f32 v[4:5], v[6:7], v[82:83] op_sel:[1,0] op_sel_hi:[0,1]
	v_add_f32_e32 v4, v4, v5
	v_xor_b32_e32 v7, 0x80000000, v4
	v_cvt_pk_bf16_f32 v7, v80, v7
	v_mul_f32_e32 v80, v73, v77
	v_pk_fma_f32 v[80:81], v[72:73], v[76:77], v[80:81] op_sel_hi:[1,1,0] neg_lo:[0,0,1] neg_hi:[0,0,1]
	v_pk_mul_f32 v[72:73], v[72:73], v[76:77] op_sel:[1,0] op_sel_hi:[0,1]
	v_add_f32_e32 v72, v72, v73
	v_xor_b32_e32 v76, 0x80000000, v72
	v_mul_f32_e32 v72, v75, v79
	v_pk_fma_f32 v[72:73], v[74:75], v[78:79], v[72:73] op_sel_hi:[1,1,0] neg_lo:[0,0,1] neg_hi:[0,0,1]
	v_pk_mul_f32 v[74:75], v[74:75], v[78:79] op_sel:[1,0] op_sel_hi:[0,1]
	v_add_f32_e32 v73, v74, v75
	v_mul_f32_e32 v74, v9, v69
	v_pk_fma_f32 v[74:75], v[8:9], v[68:69], v[74:75] op_sel_hi:[1,1,0] neg_lo:[0,0,1] neg_hi:[0,0,1]
	v_pk_mul_f32 v[8:9], v[8:9], v[68:69] op_sel:[1,0] op_sel_hi:[0,1]
	v_add_f32_e32 v8, v8, v9
	v_xor_b32_e32 v75, 0x80000000, v8
	v_mul_f32_e32 v8, v11, v71
	v_pk_fma_f32 v[68:69], v[10:11], v[70:71], v[8:9] op_sel_hi:[1,1,0] neg_lo:[0,0,1] neg_hi:[0,0,1]
	v_pk_mul_f32 v[8:9], v[10:11], v[70:71] op_sel:[1,0] op_sel_hi:[0,1]
	v_add_f32_e32 v8, v8, v9
	v_xor_b32_e32 v11, 0x80000000, v8
	v_cvt_pk_bf16_f32 v11, v68, v11
	v_mul_f32_e32 v68, v61, v65
	v_pk_fma_f32 v[68:69], v[60:61], v[64:65], v[68:69] op_sel_hi:[1,1,0] neg_lo:[0,0,1] neg_hi:[0,0,1]
	v_pk_mul_f32 v[60:61], v[60:61], v[64:65] op_sel:[1,0] op_sel_hi:[0,1]
	v_add_f32_e32 v60, v60, v61
	v_xor_b32_e32 v64, 0x80000000, v60
	v_mul_f32_e32 v60, v63, v67
	v_pk_fma_f32 v[60:61], v[62:63], v[66:67], v[60:61] op_sel_hi:[1,1,0] neg_lo:[0,0,1] neg_hi:[0,0,1]
	v_pk_mul_f32 v[62:63], v[62:63], v[66:67] op_sel:[1,0] op_sel_hi:[0,1]
	v_add_f32_e32 v61, v62, v63
	v_mul_f32_e32 v62, v13, v57
	v_pk_fma_f32 v[62:63], v[12:13], v[56:57], v[62:63] op_sel_hi:[1,1,0] neg_lo:[0,0,1] neg_hi:[0,0,1]
	v_pk_mul_f32 v[12:13], v[12:13], v[56:57] op_sel:[1,0] op_sel_hi:[0,1]
	v_add_f32_e32 v12, v12, v13
	v_xor_b32_e32 v63, 0x80000000, v12
	v_mul_f32_e32 v12, v15, v59
	v_pk_fma_f32 v[56:57], v[14:15], v[58:59], v[12:13] op_sel_hi:[1,1,0] neg_lo:[0,0,1] neg_hi:[0,0,1]
	v_pk_mul_f32 v[12:13], v[14:15], v[58:59] op_sel:[1,0] op_sel_hi:[0,1]
	v_add_f32_e32 v12, v12, v13
	v_xor_b32_e32 v15, 0x80000000, v12
	v_cvt_pk_bf16_f32 v15, v56, v15
	v_mul_f32_e32 v56, v25, v29
	v_pk_fma_f32 v[56:57], v[24:25], v[28:29], v[56:57] op_sel_hi:[1,1,0] neg_lo:[0,0,1] neg_hi:[0,0,1]
	v_pk_mul_f32 v[24:25], v[24:25], v[28:29] op_sel:[1,0] op_sel_hi:[0,1]
	v_add_f32_e32 v24, v24, v25
	v_xor_b32_e32 v28, 0x80000000, v24
	v_mul_f32_e32 v24, v27, v31
	v_pk_fma_f32 v[24:25], v[26:27], v[30:31], v[24:25] op_sel_hi:[1,1,0] neg_lo:[0,0,1] neg_hi:[0,0,1]
	v_pk_mul_f32 v[26:27], v[26:27], v[30:31] op_sel:[1,0] op_sel_hi:[0,1]
	v_add_f32_e32 v25, v26, v27
	v_mul_f32_e32 v26, v17, v21
	v_pk_fma_f32 v[26:27], v[16:17], v[20:21], v[26:27] op_sel_hi:[1,1,0] neg_lo:[0,0,1] neg_hi:[0,0,1]
	v_pk_mul_f32 v[16:17], v[16:17], v[20:21] op_sel:[1,0] op_sel_hi:[0,1]
	v_add_f32_e32 v16, v16, v17
	v_xor_b32_e32 v27, 0x80000000, v16
	v_mul_f32_e32 v16, v19, v23
	v_pk_fma_f32 v[20:21], v[18:19], v[22:23], v[16:17] op_sel_hi:[1,1,0] neg_lo:[0,0,1] neg_hi:[0,0,1]
	v_pk_mul_f32 v[16:17], v[18:19], v[22:23] op_sel:[1,0] op_sel_hi:[0,1]
	v_add_f32_e32 v16, v16, v17
	v_cvt_pk_bf16_f32 v12, v68, v64
	v_xor_b32_e32 v19, 0x80000000, v16
	v_mov_b32_e32 v64, v35
	v_mov_b32_e32 v65, v32
	v_mov_b32_e32 v66, v33
	v_mov_b32_e32 v67, v35
	v_cvt_pk_bf16_f32 v14, v62, v63
	v_cvt_pk_bf16_f32 v19, v20, v19
	v_mov_b32_e32 v62, v33
	v_mov_b32_e32 v63, v34
	v_pk_mul_f32 v[20:21], v[46:47], v[64:65]
	v_pk_mul_f32 v[22:23], v[46:47], v[66:67] op_sel:[1,0]
	v_mov_b32_e32 v33, v34
	v_pk_fma_f32 v[20:21], v[46:47], v[62:63], v[20:21] op_sel:[0,0,1] op_sel_hi:[1,1,0]
	v_pk_fma_f32 v[22:23], v[46:47], v[32:33], v[22:23] op_sel_hi:[0,1,1] neg_lo:[0,0,1] neg_hi:[0,0,1]
	v_xor_b32_e32 v25, 0x80000000, v25
	v_cndmask_b32_e64 v21, v21, v23, s[8:9]
	v_cndmask_b32_e64 v20, v20, v22, s[8:9]
	v_cvt_pk_bf16_f32 v17, v24, v25
	v_cvt_pk_bf16_f32 v23, v20, v21
	v_pk_mul_f32 v[20:21], v[64:65], v[44:45]
	v_pk_mul_f32 v[24:25], v[66:67], v[44:45] op_sel:[0,1]
	v_pk_fma_f32 v[20:21], v[62:63], v[44:45], v[20:21] op_sel:[0,0,1] op_sel_hi:[1,1,0]
	v_pk_fma_f32 v[24:25], v[32:33], v[44:45], v[24:25] op_sel_hi:[1,0,1] neg_lo:[0,0,1] neg_hi:[0,0,1]
	v_cvt_pk_bf16_f32 v18, v26, v27
	v_cndmask_b32_e64 v21, v21, v25, s[8:9]
	v_cndmask_b32_e64 v20, v20, v24, s[8:9]
	v_cvt_pk_bf16_f32 v27, v20, v21
	v_pk_mul_f32 v[20:21], v[64:65], v[38:39]
	v_pk_mul_f32 v[24:25], v[66:67], v[38:39] op_sel:[0,1]
	v_pk_fma_f32 v[20:21], v[62:63], v[38:39], v[20:21] op_sel:[0,0,1] op_sel_hi:[1,1,0]
	v_pk_fma_f32 v[24:25], v[32:33], v[38:39], v[24:25] op_sel_hi:[1,0,1] neg_lo:[0,0,1] neg_hi:[0,0,1]
	v_mov_b32_e32 v34, v55
	v_cndmask_b32_e64 v21, v21, v25, s[8:9]
	v_cndmask_b32_e64 v20, v20, v24, s[8:9]
	v_mov_b32_e32 v35, v52
	v_mov_b32_e32 v68, v53
	v_mov_b32_e32 v69, v55
	v_cvt_pk_bf16_f32 v16, v56, v28
	v_mov_b32_e32 v56, v53
	v_mov_b32_e32 v57, v54
	v_cvt_pk_bf16_f32 v31, v20, v21
	v_pk_mul_f32 v[20:21], v[46:47], v[34:35]
	v_pk_mul_f32 v[24:25], v[46:47], v[68:69] op_sel:[1,0]
	v_mov_b32_e32 v53, v54
	v_pk_fma_f32 v[20:21], v[46:47], v[56:57], v[20:21] op_sel:[0,0,1] op_sel_hi:[1,1,0]
	v_pk_fma_f32 v[24:25], v[46:47], v[52:53], v[24:25] op_sel_hi:[0,1,1] neg_lo:[0,0,1] neg_hi:[0,0,1]
	v_cndmask_b32_e64 v21, v21, v25, s[8:9]
	v_cndmask_b32_e64 v20, v20, v24, s[8:9]
	v_pk_mul_f32 v[24:25], v[34:35], v[44:45]
	v_pk_mul_f32 v[28:29], v[68:69], v[44:45] op_sel:[0,1]
	v_pk_fma_f32 v[24:25], v[56:57], v[44:45], v[24:25] op_sel:[0,0,1] op_sel_hi:[1,1,0]
	v_pk_fma_f32 v[28:29], v[52:53], v[44:45], v[28:29] op_sel_hi:[1,0,1] neg_lo:[0,0,1] neg_hi:[0,0,1]
	v_cvt_pk_bf16_f32 v20, v20, v21
	v_cndmask_b32_e64 v21, v25, v29, s[8:9]
	v_cndmask_b32_e64 v22, v24, v28, s[8:9]
	v_pk_mul_f32 v[28:29], v[34:35], v[38:39]
	v_pk_mul_f32 v[54:55], v[68:69], v[38:39] op_sel:[0,1]
	v_pk_fma_f32 v[28:29], v[56:57], v[38:39], v[28:29] op_sel:[0,0,1] op_sel_hi:[1,1,0]
	v_pk_fma_f32 v[54:55], v[52:53], v[38:39], v[54:55] op_sel_hi:[1,0,1] neg_lo:[0,0,1] neg_hi:[0,0,1]
	v_cvt_pk_bf16_f32 v24, v22, v21
	v_cndmask_b32_e64 v21, v29, v55, s[8:9]
	v_cndmask_b32_e64 v22, v28, v54, s[8:9]
	v_pk_mul_f32 v[34:35], v[34:35], v[36:37]
	v_pk_mul_f32 v[54:55], v[68:69], v[36:37] op_sel:[0,1]
	v_pk_fma_f32 v[34:35], v[56:57], v[36:37], v[34:35] op_sel:[0,0,1] op_sel_hi:[1,1,0]
	v_pk_fma_f32 v[52:53], v[52:53], v[36:37], v[54:55] op_sel_hi:[1,0,1] neg_lo:[0,0,1] neg_hi:[0,0,1]
	v_mov_b32_e32 v54, v49
	v_cndmask_b32_e64 v68, v35, v53, s[8:9]
	v_cndmask_b32_e64 v69, v34, v52, s[8:9]
	v_mov_b32_e32 v34, v51
	v_mov_b32_e32 v35, v48
	v_mov_b32_e32 v55, v51
	v_mov_b32_e32 v58, v49
	v_mov_b32_e32 v59, v50
	v_pk_mul_f32 v[52:53], v[46:47], v[34:35]
	v_pk_mul_f32 v[56:57], v[46:47], v[54:55] op_sel:[1,0]
	v_mov_b32_e32 v49, v50
	v_pk_fma_f32 v[52:53], v[46:47], v[58:59], v[52:53] op_sel:[0,0,1] op_sel_hi:[1,1,0]
	v_pk_fma_f32 v[50:51], v[46:47], v[48:49], v[56:57] op_sel_hi:[0,1,1] neg_lo:[0,0,1] neg_hi:[0,0,1]
	v_cvt_pk_bf16_f32 v28, v22, v21
	v_cndmask_b32_e64 v21, v53, v51, s[8:9]
	v_cndmask_b32_e64 v22, v52, v50, s[8:9]
	v_pk_mul_f32 v[50:51], v[34:35], v[44:45]
	v_pk_mul_f32 v[52:53], v[54:55], v[44:45] op_sel:[0,1]
	v_pk_fma_f32 v[50:51], v[58:59], v[44:45], v[50:51] op_sel:[0,0,1] op_sel_hi:[1,1,0]
	v_pk_fma_f32 v[52:53], v[48:49], v[44:45], v[52:53] op_sel_hi:[1,0,1] neg_lo:[0,0,1] neg_hi:[0,0,1]
	v_cvt_pk_bf16_f32 v21, v22, v21
	v_cndmask_b32_e64 v22, v51, v53, s[8:9]
	v_cndmask_b32_e64 v25, v50, v52, s[8:9]
	v_pk_mul_f32 v[50:51], v[34:35], v[38:39]
	v_pk_mul_f32 v[52:53], v[54:55], v[38:39] op_sel:[0,1]
	v_pk_fma_f32 v[50:51], v[58:59], v[38:39], v[50:51] op_sel:[0,0,1] op_sel_hi:[1,1,0]
	v_pk_fma_f32 v[52:53], v[48:49], v[38:39], v[52:53] op_sel_hi:[1,0,1] neg_lo:[0,0,1] neg_hi:[0,0,1]
	v_cvt_pk_bf16_f32 v25, v25, v22
	v_cndmask_b32_e64 v22, v51, v53, s[8:9]
	v_cndmask_b32_e64 v26, v50, v52, s[8:9]
	v_pk_mul_f32 v[34:35], v[34:35], v[36:37]
	v_pk_mul_f32 v[50:51], v[54:55], v[36:37] op_sel:[0,1]
	v_pk_fma_f32 v[34:35], v[58:59], v[36:37], v[34:35] op_sel:[0,0,1] op_sel_hi:[1,1,0]
	v_pk_fma_f32 v[48:49], v[48:49], v[36:37], v[50:51] op_sel_hi:[1,0,1] neg_lo:[0,0,1] neg_hi:[0,0,1]
	v_xor_b32_e32 v61, 0x80000000, v61
	v_cndmask_b32_e64 v54, v35, v49, s[8:9]
	v_cndmask_b32_e64 v55, v34, v48, s[8:9]
	v_mov_b32_e32 v34, v43
	v_mov_b32_e32 v35, v40
	v_mov_b32_e32 v50, v41
	v_mov_b32_e32 v51, v43
	v_cvt_pk_bf16_f32 v13, v60, v61
	v_mov_b32_e32 v60, v41
	v_mov_b32_e32 v61, v42
	v_pk_mul_f32 v[48:49], v[46:47], v[34:35]
	v_pk_mul_f32 v[52:53], v[46:47], v[50:51] op_sel:[1,0]
	v_mov_b32_e32 v41, v42
	v_pk_fma_f32 v[48:49], v[46:47], v[60:61], v[48:49] op_sel:[0,0,1] op_sel_hi:[1,1,0]
	v_pk_fma_f32 v[42:43], v[46:47], v[40:41], v[52:53] op_sel_hi:[0,1,1] neg_lo:[0,0,1] neg_hi:[0,0,1]
	v_cvt_pk_bf16_f32 v29, v26, v22
	v_cndmask_b32_e64 v22, v49, v43, s[8:9]
	v_cndmask_b32_e64 v26, v48, v42, s[8:9]
	v_pk_mul_f32 v[42:43], v[34:35], v[44:45]
	v_pk_mul_f32 v[46:47], v[50:51], v[44:45] op_sel:[0,1]
	v_pk_fma_f32 v[42:43], v[60:61], v[44:45], v[42:43] op_sel:[0,0,1] op_sel_hi:[1,1,0]
	v_pk_fma_f32 v[44:45], v[40:41], v[44:45], v[46:47] op_sel_hi:[1,0,1] neg_lo:[0,0,1] neg_hi:[0,0,1]
	v_cvt_pk_bf16_f32 v22, v26, v22
	v_cndmask_b32_e64 v26, v43, v45, s[8:9]
	v_cndmask_b32_e64 v30, v42, v44, s[8:9]
	v_pk_mul_f32 v[42:43], v[34:35], v[38:39]
	v_pk_mul_f32 v[44:45], v[50:51], v[38:39] op_sel:[0,1]
	v_pk_fma_f32 v[42:43], v[60:61], v[38:39], v[42:43] op_sel:[0,0,1] op_sel_hi:[1,1,0]
	v_pk_fma_f32 v[38:39], v[40:41], v[38:39], v[44:45] op_sel_hi:[1,0,1] neg_lo:[0,0,1] neg_hi:[0,0,1]
	s_lshl_b32 s0, s35, 11
	v_cvt_pk_bf16_f32 v26, v30, v26
	v_cndmask_b32_e64 v30, v43, v39, s[8:9]
	v_cndmask_b32_e64 v38, v42, v38, s[8:9]
	s_and_b32 s0, s0, 0x8000
	v_cvt_pk_bf16_f32 v30, v38, v30
	v_pk_mul_f32 v[34:35], v[34:35], v[36:37]
	v_pk_mul_f32 v[38:39], v[50:51], v[36:37] op_sel:[0,1]
	v_add_u32_e32 v48, s0, v134
	v_pk_fma_f32 v[34:35], v[60:61], v[36:37], v[34:35] op_sel:[0,0,1] op_sel_hi:[1,1,0]
	v_pk_fma_f32 v[38:39], v[40:41], v[36:37], v[38:39] op_sel_hi:[1,0,1] neg_lo:[0,0,1] neg_hi:[0,0,1]
	v_ashrrev_i32_e32 v49, 31, v48
	v_cndmask_b32_e64 v40, v35, v39, s[8:9]
	v_cndmask_b32_e64 v41, v34, v38, s[8:9]
	v_pk_mul_f32 v[34:35], v[64:65], v[36:37]
	v_lshlrev_b64 v[64:65], 11, v[48:49]
	v_add_u32_e32 v48, s0, v135
	v_ashrrev_i32_e32 v49, 31, v48
	v_pk_mul_f32 v[38:39], v[66:67], v[36:37] op_sel:[0,1]
	v_lshlrev_b64 v[66:67], 11, v[48:49]
	v_add_u32_e32 v48, s0, v136
	v_ashrrev_i32_e32 v49, 31, v48
	v_cvt_pk_bf16_f32 v6, v86, v87
	v_lshlrev_b64 v[86:87], 11, v[48:49]
	v_add_u32_e32 v48, s0, v137
	v_ashrrev_i32_e32 v49, 31, v48
	s_lshl_b32 s0, s49, 4
	v_cvt_pk_bf16_f32 v4, v190, v88
	v_lshlrev_b64 v[88:89], 11, v[48:49]
	v_and_or_b32 v48, s0, 16, v110
	v_lshl_or_b32 v52, v48, 11, v113
	s_ashr_i32 s59, s58, 31
	s_lshl_b64 s[0:1], s[58:59], 1
	v_readlane_b32 s2, v251, 20
	v_add_u32_e32 v48, v52, v120
	v_xor_b32_e32 v73, 0x80000000, v73
	v_readlane_b32 s3, v251, 21
	s_add_u32 s2, s2, s0
	v_ashrrev_i32_e32 v49, 31, v48
	v_cvt_pk_bf16_f32 v9, v72, v73
	s_addc_u32 s3, s3, s1
	v_lshlrev_b64 v[50:51], 11, v[48:49]
	v_lshl_add_u64 v[72:73], v[48:49], 4, s[50:51]
	v_add_u32_e32 v48, v52, v122
	v_lshl_add_u64 v[50:51], s[2:3], 0, v[50:51]
	v_ashrrev_i32_e32 v49, 31, v48
	v_lshl_add_u64 v[70:71], v[50:51], 0, v[96:97]
	v_lshlrev_b64 v[50:51], 11, v[48:49]
	v_pk_fma_f32 v[34:35], v[62:63], v[36:37], v[34:35] op_sel:[0,0,1] op_sel_hi:[1,1,0]
	v_pk_fma_f32 v[32:33], v[32:33], v[36:37], v[38:39] op_sel_hi:[1,0,1] neg_lo:[0,0,1] neg_hi:[0,0,1]
	v_lshl_add_u64 v[50:51], s[2:3], 0, v[50:51]
	v_cvt_pk_bf16_f32 v8, v80, v76
	v_cvt_pk_bf16_f32 v10, v74, v75
	v_cndmask_b32_e64 v35, v35, v33, s[8:9]
	v_cvt_pk_bf16_f32 v33, v55, v54
	v_lshl_add_u64 v[74:75], v[50:51], 0, v[96:97]
	v_lshl_add_u64 v[76:77], v[48:49], 4, s[50:51]
	global_load_dwordx4 v[48:51], v[70:71], off
	global_load_dwordx4 v[52:55], v[72:73], off
	global_load_dwordx4 v[56:59], v[74:75], off
	global_load_dwordx4 v[60:63], v[76:77], off
	v_lshl_add_u64 v[64:65], v[64:65], 0, s[0:1]
	v_xor_b32_e32 v85, 0x80000000, v85
	v_lshl_add_u64 v[82:83], v[98:99], 0, v[64:65]
	v_lshl_add_u64 v[64:65], v[66:67], 0, s[0:1]
	v_cvt_pk_bf16_f32 v5, v84, v85
	v_lshl_add_u64 v[84:85], v[98:99], 0, v[64:65]
	v_lshl_add_u64 v[64:65], v[86:87], 0, s[0:1]
	v_cndmask_b32_e64 v36, v34, v32, s[8:9]
	v_cvt_pk_bf16_f32 v32, v69, v68
	s_waitcnt lgkmcnt(0)
	v_cndmask_b32_e64 v68, v101, -v101, s[8:9]
	v_lshl_add_u64 v[86:87], v[98:99], 0, v[64:65]
	v_lshl_add_u64 v[64:65], v[88:89], 0, s[0:1]
	v_cvt_pk_bf16_f32 v34, v41, v40
	v_cvt_pk_bf16_f32 v35, v36, v35
	v_cvt_pk_bf16_f32 v36, v182, v181
	v_cvt_pk_bf16_f32 v37, v184, v183
	v_cvt_pk_bf16_f32 v38, v186, v185
	v_cvt_pk_bf16_f32 v39, v188, v187
	v_cvt_pk_bf16_f32 v40, v174, v169
	v_cvt_pk_bf16_f32 v41, v176, v175
	v_cvt_pk_bf16_f32 v42, v178, v177
	v_cvt_pk_bf16_f32 v43, v180, v179
	v_cvt_pk_bf16_f32 v44, v103, v102
	v_cvt_pk_bf16_f32 v45, v105, v104
	v_cvt_pk_bf16_f32 v46, v107, v106
	v_cvt_pk_bf16_f32 v47, v167, v166
	v_mov_b32_e32 v101, v100
	v_mov_b32_e32 v78, v100
	v_mov_b32_e32 v79, v100
	v_mov_b32_e32 v69, v68
	v_mov_b32_e32 v80, v68
	v_mov_b32_e32 v81, v68
	v_lshl_add_u64 v[88:89], v[98:99], 0, v[64:65]
	v_mov_b32_e32 v64, v97
	v_mov_b32_e32 v65, v97
	v_mov_b32_e32 v66, v97
	v_mov_b32_e32 v67, v97
	s_mov_b32 s36, 0
	s_waitcnt vmcnt(0)
	s_branch .LBB0_918

.LBB0_918:
	s_waitcnt vmcnt(18)
	v_mov_b32_e32 v90, v53
	v_mov_b32_e32 v91, v54
	v_mov_b32_e32 v102, v52
	v_mov_b32_e32 v103, v55
	v_pk_add_f32 v[90:91], v[90:91], v[102:103]
	v_lshlrev_b32_e32 v102, 16, v48
	v_add_f32_e32 v90, v90, v91
	v_fmamk_f32 v90, v90, 0x3a800000, v207
	v_rsq_f32_e32 v90, v90
	v_and_b32_e32 v103, 0xffff0000, v48
	v_lshlrev_b32_e32 v104, 16, v49
	v_and_b32_e32 v105, 0xffff0000, v49
	s_bitcmp1_b32 s36, 0
	v_pk_mul_f32 v[102:103], v[90:91], v[102:103] op_sel_hi:[0,1]
	v_pk_mul_f32 v[104:105], v[90:91], v[104:105] op_sel_hi:[0,1]
	s_cselect_b32 s37, 0x4400, 0
	v_cvt_pk_bf16_f32 v102, v102, v103
	v_cvt_pk_bf16_f32 v103, v104, v105
	v_lshlrev_b32_e32 v104, 16, v50
	v_and_b32_e32 v105, 0xffff0000, v50
	v_lshlrev_b32_e32 v106, 16, v51
	v_and_b32_e32 v107, 0xffff0000, v51
	s_add_i32 s0, s37, 0
	v_pk_mul_f32 v[104:105], v[90:91], v[104:105] op_sel_hi:[0,1]
	v_pk_mul_f32 v[90:91], v[90:91], v[106:107] op_sel_hi:[0,1]
	v_cvt_pk_bf16_f32 v104, v104, v105
	v_cvt_pk_bf16_f32 v105, v90, v91
	v_add_u32_e32 v90, s0, v115
	v_add3_u32 v166, v90, v116, v114
	v_add_u32_e32 v90, v166, v121
	ds_write_b128 v90, v[102:105] offset:24576
	s_waitcnt vmcnt(16)
	v_mov_b32_e32 v90, v61
	v_mov_b32_e32 v91, v62
	v_mov_b32_e32 v102, v60
	v_mov_b32_e32 v103, v63
	v_pk_add_f32 v[90:91], v[90:91], v[102:103]
	v_lshlrev_b32_e32 v102, 16, v56
	v_add_f32_e32 v90, v90, v91
	v_fmamk_f32 v90, v90, 0x3a800000, v207
	v_rsq_f32_e32 v90, v90
	v_and_b32_e32 v103, 0xffff0000, v56
	v_lshlrev_b32_e32 v104, 16, v57
	v_and_b32_e32 v105, 0xffff0000, v57
	v_pk_mul_f32 v[102:103], v[90:91], v[102:103] op_sel_hi:[0,1]
	v_pk_mul_f32 v[104:105], v[90:91], v[104:105] op_sel_hi:[0,1]
	s_cmp_eq_u32 s36, 63
	v_readlane_b32 s38, v251, 11
	v_cvt_pk_bf16_f32 v102, v102, v103
	v_cvt_pk_bf16_f32 v103, v104, v105
	v_lshlrev_b32_e32 v104, 16, v58
	v_and_b32_e32 v105, 0xffff0000, v58
	v_lshlrev_b32_e32 v106, 16, v59
	v_and_b32_e32 v107, 0xffff0000, v59
	s_cselect_b64 s[0:1], -1, 0
	s_lshl_b32 s2, s36, 5
	v_readlane_b32 s39, v251, 12
	v_pk_mul_f32 v[104:105], v[90:91], v[104:105] op_sel_hi:[0,1]
	v_pk_mul_f32 v[90:91], v[90:91], v[106:107] op_sel_hi:[0,1]
	s_mov_b32 s41, s39
	s_add_i32 s40, s2, 32
	v_writelane_b32 v251, s38, 11
	v_cvt_pk_bf16_f32 v104, v104, v105
	v_cvt_pk_bf16_f32 v105, v90, v91
	v_add_u32_e32 v90, v166, v123
	s_lshl_b64 s[2:3], s[40:41], 11
	v_writelane_b32 v251, s39, 12
	s_lshl_b64 s[38:39], s[40:41], 4
	ds_write_b128 v90, v[102:105] offset:24576
	v_lshl_add_u64 v[90:91], v[70:71], 0, s[2:3]
	v_lshl_add_u64 v[102:103], v[72:73], 0, s[38:39]
	v_lshl_add_u64 v[104:105], v[74:75], 0, s[2:3]
	v_lshl_add_u64 v[106:107], v[76:77], 0, s[38:39]
	v_add_u32_e32 v166, s37, v138
	s_mov_b64 s[2:3], 0
	s_mov_b32 s37, 0
	s_branch .LBB0_920
